# prep rows: rope cos/sin table loads hoisted to the top of the row iteration (shared by q and k blocks) instead of exposed waits mid-row
# speedup vs baseline: 1.0267x; 1.0010x over previous
.LBB0_591:
	s_or_b64 exec, exec, s[56:57]
	v_readlane_b32 s84, v254, 52
	v_readlane_b32 s85, v254, 53
	v_lshrrev_b32_e32 v234, 6, v143
	v_and_b32_e32 v235, 63, v0
	v_cndmask_b32_e64 v236, v235, v234, s[44:45]
	v_lshl_or_b32 v236, v236, 6, v75
	v_add_u32_e32 v237, 0x1000, v236
	v_cndmask_b32_e64 v234, v234, v235, s[46:47]
	v_lshlrev_b32_e32 v234, 5, v234
	v_add_u32_e32 v234, 0x2000, v234
	global_load_dwordx4 v[202:205], v237, s[84:85]
	global_load_dwordx4 v[206:209], v237, s[84:85] offset:16
	global_load_dwordx4 v[210:213], v236, s[84:85]
	global_load_dwordx4 v[214:217], v236, s[84:85] offset:16
	global_load_dwordx4 v[218:221], v234, s[84:85] offset:2064
	global_load_dwordx4 v[222:225], v234, s[84:85] offset:2048
	global_load_dwordx4 v[226:229], v234, s[84:85] offset:16
	global_load_dwordx4 v[230:233], v234, s[84:85]
	ds_read_b128 v[66:69], v188 offset:18432
	ds_read_b128 v[134:137], v188 offset:18448
	s_waitcnt vmcnt(11)
	v_lshlrev_b32_e32 v70, 16, v60
	v_and_b32_e32 v71, 0xffff0000, v60
	v_lshlrev_b32_e32 v60, 16, v61
	v_and_b32_e32 v61, 0xffff0000, v61
	v_pk_mul_f32 v[144:145], v[70:71], v[70:71]
	v_pk_mul_f32 v[146:147], v[60:61], v[60:61]
	v_add_f32_e32 v141, v144, v145
	v_lshlrev_b32_e32 v138, 16, v62
	v_and_b32_e32 v139, 0xffff0000, v62
	v_add_f32_e32 v141, v146, v141
	v_pk_mul_f32 v[148:149], v[138:139], v[138:139]
	v_add_f32_e32 v141, v147, v141
	v_and_b32_e32 v64, 0xffff0000, v63
	v_lshlrev_b32_e32 v65, 16, v63
	v_add_f32_e32 v141, v148, v141
	v_cmp_lt_i32_e32 vcc, v185, v182
	v_pk_mul_f32 v[62:63], v[64:65], v[64:65]
	v_add_f32_e32 v141, v149, v141
	v_cndmask_b32_e32 v140, v179, v185, vcc
	v_add_f32_e32 v63, v63, v141
	v_lshlrev_b32_e32 v140, 2, v140
	v_add_f32_e32 v62, v62, v63
	ds_bpermute_b32 v63, v140, v62
	v_cmp_lt_i32_e32 vcc, v186, v182
	s_waitcnt lgkmcnt(0)
	v_add_f32_e32 v62, v62, v63
	v_cndmask_b32_e32 v141, v179, v186, vcc
	v_lshlrev_b32_e32 v141, 2, v141
	ds_bpermute_b32 v63, v141, v62
	v_cmp_lt_i32_e32 vcc, v187, v182
	s_waitcnt lgkmcnt(0)
	v_add_f32_e32 v62, v62, v63
	v_cndmask_b32_e32 v142, v179, v187, vcc
	v_lshlrev_b32_e32 v142, 2, v142
	ds_bpermute_b32 v63, v142, v62
	s_waitcnt lgkmcnt(0)
	v_add_f32_e32 v62, v62, v63
	v_fmamk_f32 v62, v62, 0x3c800000, v174
	v_rsq_f32_e32 v62, v62
	s_nop 0
	v_pk_mul_f32 v[70:71], v[62:63], v[70:71] op_sel_hi:[0,1]
	v_pk_mul_f32 v[60:61], v[62:63], v[60:61] op_sel_hi:[0,1]
	v_pk_mul_f32 v[138:139], v[62:63], v[138:139] op_sel_hi:[0,1]
	v_pk_mul_f32 v[144:145], v[62:63], v[64:65] op_sel_hi:[0,1]
	s_waitcnt vmcnt(0) lgkmcnt(0)
	v_pk_mul_f32 v[66:67], v[66:67], v[70:71]
	v_pk_mul_f32 v[64:65], v[68:69], v[60:61]
	s_nop 0
	v_pk_mul_f32 v[62:63], v[134:135], v[138:139]
	v_pk_mul_f32 v[60:61], v[144:145], v[136:137] op_sel:[1,0] op_sel_hi:[0,1]
	ds_bpermute_b32 v70, v141, v66
	ds_bpermute_b32 v71, v141, v67
	ds_bpermute_b32 v136, v141, v64
	ds_bpermute_b32 v137, v141, v65
	ds_bpermute_b32 v68, v141, v62
	ds_bpermute_b32 v69, v141, v63
	ds_bpermute_b32 v134, v141, v60
	ds_bpermute_b32 v135, v141, v61
	v_lshrrev_b32_e32 v144, 6, v143
	v_and_b32_e32 v145, 63, v0
	v_cndmask_b32_e64 v138, v145, v144, s[44:45]
	s_and_saveexec_b64 s[56:57], s[54:55]
	s_cbranch_execz .LBB0_593
	v_readlane_b32 s80, v254, 48
	v_readlane_b32 s84, v254, 52
	v_readlane_b32 s85, v254, 53
	v_readlane_b32 s81, v254, 49
	v_readlane_b32 s82, v254, 50
	v_readlane_b32 s83, v254, 51
	v_readlane_b32 s86, v254, 54
	v_readlane_b32 s87, v254, 55
	s_waitcnt lgkmcnt(2)
	v_pk_mul_f32 v[68:69], v[206:207], v[68:69]
	v_pk_mul_f32 v[70:71], v[202:203], v[70:71]
	v_pk_mul_f32 v[136:137], v[204:205], v[136:137]
	s_waitcnt lgkmcnt(0)
	v_pk_mul_f32 v[134:135], v[208:209], v[134:135]
	v_cndmask_b32_e64 v137, v137, -v137, s[48:49]
	v_cndmask_b32_e64 v136, v136, -v136, s[48:49]
	v_cndmask_b32_e64 v71, v71, -v71, s[48:49]
	v_cndmask_b32_e64 v70, v70, -v70, s[48:49]
	v_cndmask_b32_e64 v135, v135, -v135, s[48:49]
	v_cndmask_b32_e64 v134, v134, -v134, s[48:49]
	v_cndmask_b32_e64 v69, v69, -v69, s[48:49]
	v_cndmask_b32_e64 v68, v68, -v68, s[48:49]
	v_pk_fma_f32 v[64:65], v[64:65], v[212:213], v[136:137]
	v_pk_fma_f32 v[60:61], v[60:61], v[216:217], v[134:135]
	v_pk_fma_f32 v[66:67], v[66:67], v[210:211], v[70:71]
	v_pk_fma_f32 v[62:63], v[62:63], v[214:215], v[68:69]
.LBB0_593:
	s_or_b64 exec, exec, s[56:57]
	v_readlane_b32 s80, v254, 48
	s_mov_b32 s2, 0x3e38aa3b
	v_readlane_b32 s84, v254, 52
	v_readlane_b32 s85, v254, 53
	v_pk_mul_f32 v[66:67], v[66:67], s[2:3] op_sel_hi:[1,0]
	v_pk_mul_f32 v[64:65], v[64:65], s[2:3] op_sel_hi:[1,0]
	v_pk_mul_f32 v[62:63], v[62:63], s[2:3] op_sel_hi:[1,0]
	s_waitcnt lgkmcnt(2)
	v_pk_mul_f32 v[68:69], v[60:61], s[2:3] op_sel_hi:[1,0]
	s_waitcnt lgkmcnt(0)
	v_lshl_add_u64 v[134:135], s[84:85], 0, v[122:123]
	s_mov_b32 s2, 0x5950000
	v_cvt_pk_bf16_f32 v61, v64, v65
	v_add_co_u32_e32 v64, vcc, s2, v134
	v_cvt_pk_bf16_f32 v60, v66, v67
	v_cvt_pk_bf16_f32 v62, v62, v63
	v_cvt_pk_bf16_f32 v63, v68, v69
	v_addc_co_u32_e32 v65, vcc, 0, v135, vcc
	global_store_dwordx4 v[64:65], v[60:63], off
	s_nop 1
	ds_read_b128 v[60:63], v188 offset:18688
	s_nop 0
	ds_read_b128 v[64:67], v188 offset:18704
	v_lshlrev_b32_e32 v70, 16, v56
	v_and_b32_e32 v71, 0xffff0000, v56
	v_lshlrev_b32_e32 v56, 16, v57
	v_and_b32_e32 v57, 0xffff0000, v57
	v_pk_mul_f32 v[146:147], v[70:71], v[70:71]
	v_pk_mul_f32 v[148:149], v[56:57], v[56:57]
	v_add_f32_e32 v139, v146, v147
	v_lshlrev_b32_e32 v136, 16, v58
	v_and_b32_e32 v137, 0xffff0000, v58
	v_add_f32_e32 v139, v148, v139
	v_pk_mul_f32 v[150:151], v[136:137], v[136:137]
	v_add_f32_e32 v139, v149, v139
	v_and_b32_e32 v68, 0xffff0000, v59
	v_lshlrev_b32_e32 v69, 16, v59
	v_add_f32_e32 v139, v150, v139
	v_pk_mul_f32 v[58:59], v[68:69], v[68:69]
	v_add_f32_e32 v139, v151, v139
	v_add_f32_e32 v59, v59, v139
	v_add_f32_e32 v58, v58, v59
	ds_bpermute_b32 v59, v140, v58
	v_readlane_b32 s81, v254, 49
	v_readlane_b32 s82, v254, 50
	v_readlane_b32 s83, v254, 51
	v_readlane_b32 s86, v254, 54
	s_waitcnt lgkmcnt(0)
	v_add_f32_e32 v58, v58, v59
	ds_bpermute_b32 v59, v141, v58
	v_readlane_b32 s87, v254, 55
	s_waitcnt lgkmcnt(0)
	v_add_f32_e32 v58, v58, v59
	ds_bpermute_b32 v59, v142, v58
	s_waitcnt lgkmcnt(0)
	v_add_f32_e32 v58, v58, v59
	v_fmamk_f32 v58, v58, 0x3c800000, v174
	v_rsq_f32_e32 v58, v58
	s_nop 0
	v_pk_mul_f32 v[70:71], v[58:59], v[70:71] op_sel_hi:[0,1]
	v_pk_mul_f32 v[56:57], v[58:59], v[56:57] op_sel_hi:[0,1]
	v_pk_mul_f32 v[136:137], v[58:59], v[136:137] op_sel_hi:[0,1]
	v_pk_mul_f32 v[58:59], v[58:59], v[68:69] op_sel_hi:[0,1]
	s_waitcnt lgkmcnt(0)
	v_pk_mul_f32 v[60:61], v[60:61], v[70:71]
	v_pk_mul_f32 v[62:63], v[62:63], v[56:57]
	s_nop 0
	v_pk_mul_f32 v[56:57], v[64:65], v[136:137]
	v_pk_mul_f32 v[58:59], v[58:59], v[66:67] op_sel:[1,0] op_sel_hi:[0,1]
	ds_bpermute_b32 v66, v141, v60
	ds_bpermute_b32 v67, v141, v61
	ds_bpermute_b32 v70, v141, v62
	ds_bpermute_b32 v71, v141, v63
	ds_bpermute_b32 v64, v141, v56
	ds_bpermute_b32 v65, v141, v57
	ds_bpermute_b32 v68, v141, v58
	ds_bpermute_b32 v69, v141, v59
	s_and_saveexec_b64 s[56:57], s[54:55]
	s_cbranch_execz .LBB0_595
	v_readlane_b32 s80, v254, 48
	v_readlane_b32 s84, v254, 52
	v_readlane_b32 s85, v254, 53
	v_readlane_b32 s81, v254, 49
	v_readlane_b32 s82, v254, 50
	v_readlane_b32 s83, v254, 51
	v_readlane_b32 s86, v254, 54
	v_readlane_b32 s87, v254, 55
	s_waitcnt lgkmcnt(2)
	v_pk_mul_f32 v[64:65], v[206:207], v[64:65]
	v_pk_mul_f32 v[66:67], v[202:203], v[66:67]
	v_pk_mul_f32 v[70:71], v[204:205], v[70:71]
	s_waitcnt lgkmcnt(0)
	v_pk_mul_f32 v[68:69], v[208:209], v[68:69]
	v_cndmask_b32_e64 v71, v71, -v71, s[48:49]
	v_cndmask_b32_e64 v70, v70, -v70, s[48:49]
	v_cndmask_b32_e64 v67, v67, -v67, s[48:49]
	v_cndmask_b32_e64 v66, v66, -v66, s[48:49]
	v_cndmask_b32_e64 v69, v69, -v69, s[48:49]
	v_cndmask_b32_e64 v68, v68, -v68, s[48:49]
	v_cndmask_b32_e64 v65, v65, -v65, s[48:49]
	v_cndmask_b32_e64 v64, v64, -v64, s[48:49]
	v_pk_fma_f32 v[62:63], v[62:63], v[212:213], v[70:71]
	v_pk_fma_f32 v[58:59], v[58:59], v[216:217], v[68:69]
	v_pk_fma_f32 v[60:61], v[60:61], v[210:211], v[66:67]
	v_pk_fma_f32 v[56:57], v[56:57], v[214:215], v[64:65]

.LBB0_609:
	v_readlane_b32 s80, v254, 48
	v_readlane_b32 s84, v254, 52
	v_readlane_b32 s85, v254, 53
	v_readlane_b32 s81, v254, 49
	v_readlane_b32 s82, v254, 50
	v_readlane_b32 s83, v254, 51
	v_readlane_b32 s86, v254, 54
	v_readlane_b32 s87, v254, 55
	s_waitcnt lgkmcnt(2)
	v_pk_mul_f32 v[54:55], v[218:219], v[54:55]
	s_waitcnt lgkmcnt(0)
	v_pk_mul_f32 v[56:57], v[220:221], v[56:57]
	v_pk_mul_f32 v[48:49], v[222:223], v[48:49]
	v_pk_mul_f32 v[50:51], v[224:225], v[50:51]
	v_cndmask_b32_e64 v57, v57, -v57, s[50:51]
	v_cndmask_b32_e64 v56, v56, -v56, s[50:51]
	v_cndmask_b32_e64 v55, v55, -v55, s[50:51]
	v_cndmask_b32_e64 v54, v54, -v54, s[50:51]
	v_cndmask_b32_e64 v51, v51, -v51, s[50:51]
	v_cndmask_b32_e64 v50, v50, -v50, s[50:51]
	v_cndmask_b32_e64 v49, v49, -v49, s[50:51]
	v_cndmask_b32_e64 v48, v48, -v48, s[50:51]
	v_pk_fma_f32 v[42:43], v[228:229], v[42:43], v[56:57]
	v_pk_fma_f32 v[46:47], v[232:233], v[46:47], v[50:51]
	v_pk_fma_f32 v[44:45], v[230:231], v[44:45], v[48:49]
	v_pk_fma_f32 v[40:41], v[226:227], v[40:41], v[54:55]
	s_or_b64 exec, exec, s[54:55]
	s_and_saveexec_b64 s[54:55], s[40:41]
	s_cbranch_execz .LBB0_568
